# adds: hand-written monotonic-counter grid barrier for the 7 syncs before phases 2..8 (first sync unchanged)
# speedup vs baseline: 1.0490x; 1.0146x over previous
; #define RUN(k, call) if (lo <= (k) && (k) < hi) { if ((k) > lo) grid.sync(); if (PHMASK & (1 << (k))) { call; } }
; __global__ void __launch_bounds__(NT, 2) fwd_kernel(Params p) {
;     ...
;   RUN(0, phase0(p, lds))
;   RUN(1, phase1(p))
;   RUN(2, phase2(p, lds))
.LBB0_82:
	s_cmp_lt_i32 s78, 3
	s_cselect_b64 s[4:5], -1, 0
	s_cmp_gt_i32 s79, 2
	s_cselect_b64 s[0:1], -1, 0
	s_and_b64 s[0:1], s[4:5], s[0:1]
	s_andn2_b64 vcc, exec, s[0:1]
	s_cbranch_vccnz .LBB0_137
	s_andn2_b64 vcc, exec, s[6:7]
	s_cbranch_vccnz .LBB0_95
	v_and_b32_e32 v1, 0x3fffffff, v0
	v_cmp_eq_u32_e32 vcc, 0, v1
	s_waitcnt lgkmcnt(0)
	s_barrier
	s_and_saveexec_b64 s[0:1], vcc
	s_cbranch_execz .LBB0_94
	buffer_wbl2 sc1
	s_load_dwordx2 s[6:7], s[74:75], 0xe0
	v_mov_b32_e32 v1, 0
	v_mov_b32_e32 v3, 1
	s_waitcnt vmcnt(0) lgkmcnt(0)
	s_add_u32 s6, s6, 0x194108
	s_addc_u32 s7, s7, 0
	global_atomic_add v1, v3, s[6:7]
.Lgb2_spin:
	global_load_dword v3, v1, s[6:7] sc1
	s_waitcnt vmcnt(0)
	v_cmp_gt_u32_e32 vcc, s72, v3
	s_cbranch_vccz .Lgb2_out
	s_sleep 1
	s_branch .Lgb2_spin

; #define RUN(k, call) if (lo <= (k) && (k) < hi) { if ((k) > lo) grid.sync(); if (PHMASK & (1 << (k))) { call; } }
; __global__ void __launch_bounds__(NT, 2) fwd_kernel(Params p) {
;     ...
;   RUN(0, phase0(p, lds))
;   RUN(1, phase1(p))
;   RUN(2, phase2(p, lds))
;   RUN(3, phase3(p, lds))
.LBB0_137:
	s_cmp_lt_i32 s78, 4
	s_cselect_b64 s[16:17], -1, 0
	s_cmp_gt_i32 s79, 3
	s_cselect_b64 s[0:1], -1, 0
	s_and_b64 s[0:1], s[16:17], s[0:1]
	s_andn2_b64 vcc, exec, s[0:1]
	s_cbranch_vccnz .LBB0_212
	s_andn2_b64 vcc, exec, s[4:5]
	s_cbranch_vccnz .LBB0_150
	v_and_b32_e32 v1, 0x3fffffff, v0
	v_cmp_eq_u32_e32 vcc, 0, v1
	s_waitcnt lgkmcnt(0)
	s_barrier
	s_and_saveexec_b64 s[0:1], vcc
	s_cbranch_execz .LBB0_149
	buffer_wbl2 sc1
	s_load_dwordx2 s[4:5], s[74:75], 0xe0
	v_mov_b32_e32 v1, 0
	v_mov_b32_e32 v3, 1
	s_waitcnt vmcnt(0) lgkmcnt(0)
	s_add_u32 s4, s4, 0x19410c
	s_addc_u32 s5, s5, 0
	global_atomic_add v1, v3, s[4:5]
.Lgb3_spin:
	global_load_dword v3, v1, s[4:5] sc1
	s_waitcnt vmcnt(0)
	v_cmp_gt_u32_e32 vcc, s72, v3
	s_cbranch_vccz .Lgb3_out
	s_sleep 1
	s_branch .Lgb3_spin

; DI void attn_item(const Params& p, char* lds, int S, const bfr* Qb, const bfr* Kb, const bfr* Vtb, int h, int q0, int tok0) {
;     ...
;   for (int kt = 0; kt < nkt; ++kt) {
;     if (kt + 2 < nkt) WAIT_V(4); else if (kt + 1 < nkt) WAIT_V(2); else WAIT_V(0);
;     RAW_BARRIER();
;     if (kt + 3 < nkt) stage((kt + 3) & 3, kt + 3);
;     const char* sb = lds + 65536 + (kt & 3) * 16384;
;     const char* kimg = sb + c * 4096;
;     const char* vimg = sb + 8192;
;     f32x16 st[2];
;     {
;       bf16x8 kf[4];
; #pragma unroll
;       for (int ks = 0; ks < 4; ++ks) kf[ks] = *(const bf16x8*)(kimg + voffK[ks]);
; #pragma unroll
;       for (int t = 0; t < 2; ++t) {
;         const float negm = -m[t];
; #pragma unroll
;         for (int i = 0; i < 16; ++i) st[t][i] = negm;
; #pragma unroll
;         for (int ks = 0; ks < 4; ++ks) st[t] = MFMA(kf[ks], *(const bf16x8*)(qimg + t * 4096 + voffK[ks]), st[t]);
;       }
;     }
; #pragma unroll
;     for (int t = 0; t < 2; ++t) {
;       float mx = st[t][0];
; #pragma unroll
;       for (int i = 1; i < 16; ++i) mx = fmaxf(mx, st[t][i]);
;       mx = fmaxf(mx, __shfl_xor(mx, 32, 64));
;       if (__any(mx > 6.f)) {
;         const float d = fmaxf(mx, 0.f);
;         const float alpha = __builtin_amdgcn_exp2f(-d);
;         m[t] += d;
;         l[t] *= alpha;
; #pragma unroll
;         for (int i = 0; i < 16; ++i) st[t][i] -= d;
; #pragma unroll
;         for (int e = 0; e < 4; ++e)
; #pragma unroll
;           for (int i = 0; i < 16; ++i) O[t][e][i] *= alpha;
;       }
;     }
;     __builtin_amdgcn_iglp_opt(0);
; #pragma unroll
;     for (int t = 0; t < 2; ++t) {
;       float rs = 0.f;
; #pragma unroll
;       for (int i = 0; i < 16; ++i) { float pv = __builtin_amdgcn_exp2f(st[t][i]); st[t][i] = pv; rs += pv; }
;       l[t] += rs;
;       bf16x8 pf[2];
; #pragma unroll
;       for (int kc = 0; kc < 2; ++kc) {
;         u32x4 pp;
;         pp[0] = pk2(st[t][kc * 8 + 0], st[t][kc * 8 + 1]); pp[1] = pk2(st[t][kc * 8 + 2], st[t][kc * 8 + 3]);
;         pp[2] = pk2(st[t][kc * 8 + 4], st[t][kc * 8 + 5]); pp[3] = pk2(st[t][kc * 8 + 6], st[t][kc * 8 + 7]);
;         pf[kc] = __builtin_bit_cast(bf16x8, pp);
;       }
; #pragma unroll
;       for (int e = 0; e < 4; ++e)
; #pragma unroll
;         for (int kc = 0; kc < 2; ++kc) O[t][e] = MFMA(*(const bf16x8*)(vimg + e * 2048 + (voffV0 ^ (kc << 5))), pf[kc], O[t][e]);
;     }
.Lfa_loop:
	s_add_i32 s4, s0, 0xc000
	s_and_b32 s4, s4, 0xc000
	s_add_i32 s4, s58, s4
	s_waitcnt vmcnt(2)
	s_add_i32 s5, s4, 0x2000
	s_mov_b32 m0, s4
	s_barrier
	s_waitcnt lgkmcnt(2)
	v_mfma_f32_32x32x16_bf16 v[148:163], v[168:171], v[196:199], 0
	global_load_lds_dwordx4 v[164:165], off
	s_mov_b32 m0, s5
	s_nop 0
	global_load_lds_dwordx4 v[166:167], off
	s_and_b32 s4, s0, 0xc000
	s_bitset1_b32 s4, 16
	ds_read_b128 v[196:199], v182 offset:4096
	v_add_u32_e32 v255, s4, v209
	v_add_u32_e32 v254, s4, v210
	v_add_f32_e32 v180, v180, v132
	v_add_f32_e32 v180, v180, v133
	v_add_f32_e32 v180, v180, v134
	v_add_f32_e32 v180, v180, v135
	s_waitcnt lgkmcnt(2)
	v_mfma_f32_32x32x16_bf16 v[148:163], v[172:175], v[218:221], v[148:163]
	ds_read_b128 v[226:229], v255 offset:8192
	ds_read_b128 v[234:237], v255 offset:10240
	v_add_f32_e32 v180, v180, v136
	ds_read_b128 v[242:245], v255 offset:12288
	v_cvt_pk_bf16_f32 v132, v132, v133
	v_cvt_pk_bf16_f32 v133, v134, v135
	v_cvt_pk_bf16_f32 v134, v136, v137
	v_cvt_pk_bf16_f32 v135, v138, v139
	v_add_f32_e32 v180, v180, v137
	s_waitcnt lgkmcnt(4)
	v_mfma_f32_32x32x16_bf16 v[148:163], v[176:179], v[192:195], v[148:163]
	ds_read_b128 v[250:253], v255 offset:14336
	ds_read_b128 v[230:233], v254 offset:8192
	ds_read_b128 v[238:241], v254 offset:10240
	v_add_f32_e32 v180, v180, v138
	v_add_f32_e32 v180, v180, v139
	v_exp_f32_e32 v140, v140
	v_exp_f32_e32 v141, v141
	v_lshl_add_u64 v[164:165], v[164:165], 0, s[50:51]
	s_waitcnt lgkmcnt(6)
	v_mfma_f32_32x32x16_bf16 v[148:163], v[188:191], v[196:199], v[148:163]
	ds_read_b128 v[246:249], v254 offset:12288
	v_exp_f32_e32 v142, v142
	ds_read_b128 v[222:225], v254 offset:14336
	v_lshl_add_u64 v[166:167], v[166:167], 0, s[52:53]
	s_add_i32 s5, s0, 0x4000
	s_and_b32 s5, s5, 0xc000
	v_exp_f32_e32 v143, v143
	s_bitset1_b32 s5, 16
	s_or_b32 s5, s5, s3
	s_waitcnt lgkmcnt(7)
	v_mfma_f32_32x32x16_bf16 v[116:131], v[226:229], v[132:135], v[116:131]
	v_exp_f32_e32 v144, v144
	v_exp_f32_e32 v145, v145
	v_add_f32_e32 v180, v180, v140
	v_add_u32_e32 v200, s5, v203
	ds_read_b128 v[168:171], v200
	s_waitcnt lgkmcnt(7)
	v_exp_f32_e32 v146, v146
	v_mfma_f32_32x32x16_bf16 v[100:115], v[234:237], v[132:135], v[100:115]
	v_exp_f32_e32 v147, v147
	v_add_f32_e32 v180, v180, v141
	v_add_u32_e32 v200, s5, v204
	ds_read_b128 v[172:175], v200
	s_waitcnt lgkmcnt(7)
	v_mfma_f32_32x32x16_bf16 v[84:99], v[242:245], v[132:135], v[84:99]
	v_add_f32_e32 v180, v180, v142
	v_add_f32_e32 v180, v180, v143
	v_add_f32_e32 v180, v180, v144
	v_add_f32_e32 v180, v180, v145
	v_add_u32_e32 v200, s5, v205
	ds_read_b128 v[176:179], v200
	s_waitcnt lgkmcnt(7)
	v_mfma_f32_32x32x16_bf16 v[68:83], v[250:253], v[132:135], v[68:83]
	v_cvt_pk_bf16_f32 v140, v140, v141
	v_cvt_pk_bf16_f32 v141, v142, v143
	v_cvt_pk_bf16_f32 v142, v144, v145
	v_cvt_pk_bf16_f32 v143, v146, v147
	v_add_f32_e32 v180, v180, v146
	v_add_f32_e32 v180, v180, v147
	v_add_u32_e32 v200, s5, v206
	ds_read_b128 v[188:191], v200
	s_waitcnt lgkmcnt(7)
	v_mfma_f32_32x32x16_bf16 v[116:131], v[230:233], v[140:143], v[116:131]
	v_exp_f32_e32 v148, v148
	v_exp_f32_e32 v149, v149
	v_exp_f32_e32 v150, v150
	s_waitcnt lgkmcnt(6)
	v_mfma_f32_32x32x16_bf16 v[100:115], v[238:241], v[140:143], v[100:115]
	v_exp_f32_e32 v151, v151
	v_add_f32_e32 v181, v181, v148
	v_exp_f32_e32 v152, v152
	v_add_f32_e32 v181, v181, v149
	v_exp_f32_e32 v153, v153
	s_waitcnt lgkmcnt(5)
	v_mfma_f32_32x32x16_bf16 v[84:99], v[246:249], v[140:143], v[84:99]
	v_add_f32_e32 v181, v181, v150
	v_exp_f32_e32 v154, v154
	v_add_f32_e32 v181, v181, v151
	v_exp_f32_e32 v155, v155
	v_add_f32_e32 v181, v181, v152
	v_add_f32_e32 v181, v181, v153
	s_waitcnt lgkmcnt(4)
	v_mfma_f32_32x32x16_bf16 v[68:83], v[222:225], v[140:143], v[68:83]
	v_cvt_pk_bf16_f32 v148, v148, v149
	v_cvt_pk_bf16_f32 v149, v150, v151
	v_cvt_pk_bf16_f32 v150, v152, v153
	v_cvt_pk_bf16_f32 v151, v154, v155
	v_add_f32_e32 v181, v181, v154
	v_add_f32_e32 v181, v181, v155
	v_exp_f32_e32 v156, v156
	v_mfma_f32_32x32x16_bf16 v[52:67], v[226:229], v[148:151], v[52:67]
	ds_read_b128 v[192:195], v185
	v_mfma_f32_32x32x16_bf16 v[36:51], v[234:237], v[148:151], v[36:51]
	v_exp_f32_e32 v157, v157
	v_exp_f32_e32 v158, v158
	ds_read_b128 v[196:199], v184
	v_mfma_f32_32x32x16_bf16 v[20:35], v[242:245], v[148:151], v[20:35]
	v_exp_f32_e32 v159, v159
	v_exp_f32_e32 v160, v160
	v_exp_f32_e32 v161, v161
	v_add_f32_e32 v181, v181, v156
	ds_read_b128 v[218:221], v183
	v_mfma_f32_32x32x16_bf16 v[4:19], v[250:253], v[148:151], v[4:19]
	v_exp_f32_e32 v162, v162
	v_exp_f32_e32 v163, v163
	v_add_f32_e32 v181, v181, v157
	s_waitcnt lgkmcnt(2)
	v_mfma_f32_32x32x16_bf16 v[132:147], v[168:171], v[192:195], 0
	ds_read_b128 v[192:195], v182
	v_add_f32_e32 v181, v181, v158
	v_add_f32_e32 v181, v181, v159
	v_add_f32_e32 v181, v181, v160
	v_add_f32_e32 v181, v181, v161
	s_waitcnt lgkmcnt(2)
	v_mfma_f32_32x32x16_bf16 v[132:147], v[172:175], v[196:199], v[132:147]
	v_cvt_pk_bf16_f32 v156, v156, v157
	v_cvt_pk_bf16_f32 v157, v158, v159
	v_cvt_pk_bf16_f32 v158, v160, v161
	v_add_f32_e32 v181, v181, v162
	v_cvt_pk_bf16_f32 v159, v162, v163
	ds_read_b128 v[196:199], v185 offset:4096
	v_add_f32_e32 v181, v181, v163
	s_waitcnt lgkmcnt(2)
	v_mfma_f32_32x32x16_bf16 v[132:147], v[176:179], v[218:221], v[132:147]
	ds_read_b128 v[218:221], v184 offset:4096
	s_add_i32 s1, s1, 1
	s_addk_i32 s0, 0x4000
	s_waitcnt lgkmcnt(2)
	v_mfma_f32_32x32x16_bf16 v[132:147], v[188:191], v[192:195], v[132:147]
	ds_read_b128 v[192:195], v183 offset:4096
	v_mfma_f32_32x32x16_bf16 v[52:67], v[230:233], v[156:159], v[52:67]
	s_nop 3
	v_mfma_f32_32x32x16_bf16 v[36:51], v[238:241], v[156:159], v[36:51]
	s_nop 3
	v_mfma_f32_32x32x16_bf16 v[20:35], v[246:249], v[156:159], v[20:35]
	v_exp_f32_e32 v132, v132
	v_exp_f32_e32 v133, v133
	v_exp_f32_e32 v134, v134
	v_mfma_f32_32x32x16_bf16 v[4:19], v[222:225], v[156:159], v[4:19]
	v_exp_f32_e32 v135, v135
	v_exp_f32_e32 v136, v136
	v_exp_f32_e32 v137, v137
	v_exp_f32_e32 v138, v138
	v_exp_f32_e32 v139, v139
	s_cmp_eq_u32 s38, s1
	s_cbranch_scc0 .Lfa_loop
	v_mov_b32_e32 v186, 0
	v_mov_b32_e32 v187, 0
	v_cmp_lt_i32_e32 vcc, v213, v214
	s_nop 1
	v_cndmask_b32_e32 v2, v212, v213, vcc
	v_lshlrev_b32_e32 v216, 2, v2
	s_setprio 0
	s_branch .LBB0_165

; #define RUN(k, call) if (lo <= (k) && (k) < hi) { if ((k) > lo) grid.sync(); if (PHMASK & (1 << (k))) { call; } }
; __global__ void __launch_bounds__(NT, 2) fwd_kernel(Params p) {
;     ...
;   RUN(0, phase0(p, lds))
;   RUN(1, phase1(p))
;   RUN(2, phase2(p, lds))
;   RUN(3, phase3(p, lds))
;   RUN(4, phase4(p, lds))
.LBB0_212:
	s_cmp_gt_i32 s78, 4
	s_cselect_b64 s[0:1], -1, 0
	s_cmp_lt_i32 s78, 5
	s_cselect_b64 s[4:5], -1, 0
	s_cmp_gt_i32 s79, 4
	s_cselect_b64 s[6:7], -1, 0
	s_and_b64 s[4:5], s[4:5], s[6:7]
	s_andn2_b64 vcc, exec, s[4:5]
	s_cbranch_vccnz .LBB0_232
	s_andn2_b64 vcc, exec, s[16:17]
	s_cbranch_vccnz .LBB0_225
	v_and_b32_e32 v1, 0x3fffffff, v0
	v_cmp_eq_u32_e32 vcc, 0, v1
	s_waitcnt lgkmcnt(0)
	s_barrier
	s_and_saveexec_b64 s[4:5], vcc
	s_cbranch_execz .LBB0_224
	buffer_wbl2 sc1
	s_load_dwordx2 s[6:7], s[74:75], 0xe0
	v_mov_b32_e32 v1, 0
	v_mov_b32_e32 v3, 1
	s_waitcnt vmcnt(0) lgkmcnt(0)
	s_add_u32 s6, s6, 0x194110
	s_addc_u32 s7, s7, 0
	global_atomic_add v1, v3, s[6:7]

; #define RUN(k, call) if (lo <= (k) && (k) < hi) { if ((k) > lo) grid.sync(); if (PHMASK & (1 << (k))) { call; } }
; __global__ void __launch_bounds__(NT, 2) fwd_kernel(Params p) {
;     ...
;   RUN(0, phase0(p, lds))
;   RUN(1, phase1(p))
;   RUN(2, phase2(p, lds))
;   RUN(3, phase3(p, lds))
;   RUN(4, phase4(p, lds))
;   RUN(5, phase5(p, lds))
.LBB0_235:
.LBB0_236:
	v_and_b32_e32 v1, 0x3fffffff, v0
	v_cmp_eq_u32_e32 vcc, 0, v1
	s_waitcnt lgkmcnt(0)
	s_barrier
	s_and_saveexec_b64 s[0:1], vcc
	s_cbranch_execz .LBB0_246
	buffer_wbl2 sc1
	s_load_dwordx2 s[4:5], s[74:75], 0xe0
	v_mov_b32_e32 v1, 0
	v_mov_b32_e32 v3, 1
	s_waitcnt vmcnt(0) lgkmcnt(0)
	s_add_u32 s4, s4, 0x194114
	s_addc_u32 s5, s5, 0
	global_atomic_add v1, v3, s[4:5]

; #define RUN(k, call) if (lo <= (k) && (k) < hi) { if ((k) > lo) grid.sync(); if (PHMASK & (1 << (k))) { call; } }
; __global__ void __launch_bounds__(NT, 2) fwd_kernel(Params p) {
;     ...
;   RUN(0, phase0(p, lds))
;   RUN(1, phase1(p))
;   RUN(2, phase2(p, lds))
;   RUN(3, phase3(p, lds))
;   RUN(4, phase4(p, lds))
;   RUN(5, phase5(p, lds))
;   RUN(6, phase_moe(p, lds, 0))
.LBB0_271:
.LBB0_272:
	v_and_b32_e32 v1, 0x3fffffff, v0
	v_cmp_eq_u32_e32 vcc, 0, v1
	s_waitcnt lgkmcnt(0)
	s_barrier
	s_and_saveexec_b64 s[0:1], vcc
	s_cbranch_execz .LBB0_282
	buffer_wbl2 sc1
	s_load_dwordx2 s[4:5], s[74:75], 0xe0
	v_mov_b32_e32 v1, 0
	v_mov_b32_e32 v3, 1
	s_waitcnt vmcnt(0) lgkmcnt(0)
	s_add_u32 s4, s4, 0x194118
	s_addc_u32 s5, s5, 0
	global_atomic_add v1, v3, s[4:5]

; #define RUN(k, call) if (lo <= (k) && (k) < hi) { if ((k) > lo) grid.sync(); if (PHMASK & (1 << (k))) { call; } }
; __global__ void __launch_bounds__(NT, 2) fwd_kernel(Params p) {
;     ...
;   RUN(0, phase0(p, lds))
;   RUN(1, phase1(p))
;   RUN(2, phase2(p, lds))
;   RUN(3, phase3(p, lds))
;   RUN(4, phase4(p, lds))
;   RUN(5, phase5(p, lds))
;   RUN(6, phase_moe(p, lds, 0))
;   RUN(7, phase_moe(p, lds, 1))
.LBB0_305:
.LBB0_306:
	v_and_b32_e32 v1, 0x3fffffff, v0
	v_cmp_eq_u32_e32 vcc, 0, v1
	s_barrier
	s_and_saveexec_b64 s[0:1], vcc
	s_cbranch_execz .LBB0_316
	buffer_wbl2 sc1
	s_load_dwordx2 s[4:5], s[74:75], 0xe0
	v_mov_b32_e32 v1, 0
	v_mov_b32_e32 v3, 1
	s_waitcnt vmcnt(0) lgkmcnt(0)
	s_add_u32 s4, s4, 0x19411c
	s_addc_u32 s5, s5, 0
	global_atomic_add v1, v3, s[4:5]

; #define RUN(k, call) if (lo <= (k) && (k) < hi) { if ((k) > lo) grid.sync(); if (PHMASK & (1 << (k))) { call; } }
; __global__ void __launch_bounds__(NT, 2) fwd_kernel(Params p) {
;     ...
;   RUN(0, phase0(p, lds))
;   RUN(1, phase1(p))
;   RUN(2, phase2(p, lds))
;   RUN(3, phase3(p, lds))
;   RUN(4, phase4(p, lds))
;   RUN(5, phase5(p, lds))
;   RUN(6, phase_moe(p, lds, 0))
;   RUN(7, phase_moe(p, lds, 1))
;   RUN(8, phase_moe(p, lds, 2))
.LBB0_400:
.LBB0_401:
	v_and_b32_e32 v1, 0x3fffffff, v0
	v_cmp_eq_u32_e32 vcc, 0, v1
	s_barrier
	s_and_saveexec_b64 s[0:1], vcc
	s_cbranch_execz .LBB0_411
	buffer_wbl2 sc1
	s_load_dwordx2 s[4:5], s[74:75], 0xe0
	v_mov_b32_e32 v1, 0
	v_mov_b32_e32 v3, 1
	s_waitcnt vmcnt(0) lgkmcnt(0)
	s_add_u32 s4, s4, 0x194120
	s_addc_u32 s5, s5, 0
	global_atomic_add v1, v3, s[4:5]
